# up GEMM epilogue: squared ReLU as max(x,0) then one packed multiply per accumulator pair (same values), 320 -> 256 VALU per unit per wave
# baseline (speedup 1.0000x reference)
; __device__ __forceinline__ u32x4 pack8(const f32x4 a, const f32x4 b) { u32x4 w; w.x = cvt_pk_bf16(a[0], a[1]); w.y = cvt_pk_bf16(a[2], a[3]); w.z = cvt_pk_bf16(b[0], b[1]); w.w = cvt_pk_bf16(b[2], b[3]); return w; }
;     __device__ __forceinline__ void run(const acc_t& acc, const Unit& u, int wr, int wc, int fr, int fq, const int A0, const int A1) const {
;         const char* ub = (const char*)(U + (size_t)(u.pm * BM + wr * 64) * FF + u.pn * BM + wc * 64); const unsigned lo = (unsigned)(fr * FF + 8 * fq) * 2u;
; #pragma unroll
;         for (int ai = A0; ai < A1; ++ai)
; #pragma unroll
;             for (int m = 0; m < 4; ++m) { char* rowp = (char*)ub + (size_t)(ai * HALF + m * 16) * FF * 2;
; #pragma unroll
;                 for (int bj = 0; bj < 2; ++bj) { f32x4 a = acc[ai][bj][m][0], b = acc[ai][bj][m][1];
; #pragma unroll
;                     for (int e = 0; e < 4; ++e) { a[e] = fmaxf(a[e] * __builtin_fabsf(a[e]), 0.f); b[e] = fmaxf(b[e] * __builtin_fabsf(b[e]), 0.f); }
;                     *(u32x4*)(rowp + 32 * bj * 2 + lo) = pack8(a, b); } }
;     }
.LBB0_898:
	v_max_f32_e32 v126, 0, v126
	v_max_f32_e32 v127, 0, v127
	v_max_f32_e32 v128, 0, v128
	v_max_f32_e32 v129, 0, v129
	v_max_f32_e32 v122, 0, v122
	v_max_f32_e32 v123, 0, v123
	v_max_f32_e32 v124, 0, v124
	v_max_f32_e32 v125, 0, v125
	v_pk_mul_f32 v[126:127], v[126:127], v[126:127]
	v_pk_mul_f32 v[128:129], v[128:129], v[128:129]
	v_pk_mul_f32 v[122:123], v[122:123], v[122:123]
	v_pk_mul_f32 v[124:125], v[124:125], v[124:125]
	v_cvt_pk_bf16_f32 v210, v126, v127
	v_cvt_pk_bf16_f32 v211, v128, v129
	v_cvt_pk_bf16_f32 v212, v122, v123
	v_cvt_pk_bf16_f32 v213, v124, v125
	s_lshl_b32 s7, s16, 8
	s_add_i32 s18, s7, s35
	s_ashr_i32 s19, s18, 31
	s_lshl_b64 s[18:19], s[18:19], 13
	s_add_u32 s7, s82, s18
	s_addc_u32 s11, s83, s19
	s_lshl_b32 s18, s49, 8
	s_ashr_i32 s19, s18, 31
	s_lshl_b64 s[18:19], s[18:19], 1
	s_add_u32 s7, s7, s18
	s_addc_u32 s11, s11, s19
	s_add_u32 s18, s7, s41
	s_addc_u32 s19, s11, 0
	v_lshl_add_u64 v[136:137], s[18:19], 0, v[130:131]
	global_store_dwordx4 v[136:137], v[210:213], off
	v_max_f32_e32 v118, 0, v118
	v_max_f32_e32 v119, 0, v119
	v_max_f32_e32 v120, 0, v120
	v_max_f32_e32 v121, 0, v121
	v_max_f32_e32 v110, 0, v110
	v_max_f32_e32 v111, 0, v111
	v_max_f32_e32 v112, 0, v112
	v_max_f32_e32 v113, 0, v113
	v_pk_mul_f32 v[118:119], v[118:119], v[118:119]
	v_pk_mul_f32 v[120:121], v[120:121], v[120:121]
	v_pk_mul_f32 v[110:111], v[110:111], v[110:111]
	v_pk_mul_f32 v[112:113], v[112:113], v[112:113]
	v_cvt_pk_bf16_f32 v214, v118, v119
	v_cvt_pk_bf16_f32 v215, v120, v121
	v_cvt_pk_bf16_f32 v216, v110, v111
	v_cvt_pk_bf16_f32 v217, v112, v113
	global_store_dwordx4 v[136:137], v[214:217], off offset:64
	v_max_f32_e32 v114, 0, v114
	v_max_f32_e32 v115, 0, v115
	v_max_f32_e32 v116, 0, v116
	v_max_f32_e32 v117, 0, v117
	v_max_f32_e32 v106, 0, v106
	v_max_f32_e32 v107, 0, v107
	v_max_f32_e32 v108, 0, v108
	v_max_f32_e32 v109, 0, v109
	v_pk_mul_f32 v[114:115], v[114:115], v[114:115]
	v_pk_mul_f32 v[116:117], v[116:117], v[116:117]
	v_pk_mul_f32 v[106:107], v[106:107], v[106:107]
	v_pk_mul_f32 v[108:109], v[108:109], v[108:109]
	v_cvt_pk_bf16_f32 v210, v114, v115
	v_cvt_pk_bf16_f32 v211, v116, v117
	v_cvt_pk_bf16_f32 v212, v106, v107
	v_cvt_pk_bf16_f32 v213, v108, v109
	v_add_co_u32_e32 v110, vcc, s42, v136
	v_addc_co_u32_e32 v111, vcc, 0, v137, vcc
	global_store_dwordx4 v[110:111], v[210:213], off
	v_max_f32_e32 v102, 0, v102
	v_max_f32_e32 v103, 0, v103
	v_max_f32_e32 v104, 0, v104
	v_max_f32_e32 v105, 0, v105
	v_max_f32_e32 v94, 0, v94
	v_max_f32_e32 v95, 0, v95
	v_max_f32_e32 v96, 0, v96
	v_max_f32_e32 v97, 0, v97
	v_pk_mul_f32 v[102:103], v[102:103], v[102:103]
	v_pk_mul_f32 v[104:105], v[104:105], v[104:105]
	v_pk_mul_f32 v[94:95], v[94:95], v[94:95]
	v_pk_mul_f32 v[96:97], v[96:97], v[96:97]
	v_cvt_pk_bf16_f32 v214, v102, v103
	v_cvt_pk_bf16_f32 v215, v104, v105
	v_cvt_pk_bf16_f32 v216, v94, v95
	v_cvt_pk_bf16_f32 v217, v96, v97
	global_store_dwordx4 v[110:111], v[214:217], off offset:64
	v_max_f32_e32 v98, 0, v98
	v_max_f32_e32 v99, 0, v99
	v_max_f32_e32 v100, 0, v100
	v_max_f32_e32 v101, 0, v101
	v_max_f32_e32 v90, 0, v90
	v_max_f32_e32 v91, 0, v91
	v_max_f32_e32 v92, 0, v92
	v_max_f32_e32 v93, 0, v93
	v_pk_mul_f32 v[98:99], v[98:99], v[98:99]
	v_pk_mul_f32 v[100:101], v[100:101], v[100:101]
	v_pk_mul_f32 v[90:91], v[90:91], v[90:91]
	v_pk_mul_f32 v[92:93], v[92:93], v[92:93]
	v_cvt_pk_bf16_f32 v210, v98, v99
	v_cvt_pk_bf16_f32 v211, v100, v101
	v_cvt_pk_bf16_f32 v212, v90, v91
	v_cvt_pk_bf16_f32 v213, v92, v93
	v_add_co_u32_e32 v94, vcc, s43, v136
	v_addc_co_u32_e32 v95, vcc, 0, v137, vcc
	global_store_dwordx4 v[94:95], v[210:213], off
	v_max_f32_e32 v86, 0, v86
	v_max_f32_e32 v87, 0, v87
	v_max_f32_e32 v88, 0, v88
	v_max_f32_e32 v89, 0, v89
	v_max_f32_e32 v78, 0, v78
	v_max_f32_e32 v79, 0, v79
	v_max_f32_e32 v80, 0, v80
	v_max_f32_e32 v81, 0, v81
	v_pk_mul_f32 v[86:87], v[86:87], v[86:87]
	v_pk_mul_f32 v[88:89], v[88:89], v[88:89]
	v_pk_mul_f32 v[78:79], v[78:79], v[78:79]
	v_pk_mul_f32 v[80:81], v[80:81], v[80:81]
	v_cvt_pk_bf16_f32 v214, v86, v87
	v_cvt_pk_bf16_f32 v215, v88, v89
	v_cvt_pk_bf16_f32 v216, v78, v79
	v_cvt_pk_bf16_f32 v217, v80, v81
	global_store_dwordx4 v[94:95], v[214:217], off offset:64
	v_max_f32_e32 v82, 0, v82
	v_max_f32_e32 v83, 0, v83
	v_max_f32_e32 v84, 0, v84
	v_max_f32_e32 v85, 0, v85
	v_max_f32_e32 v74, 0, v74
	v_max_f32_e32 v75, 0, v75
	v_max_f32_e32 v76, 0, v76
	v_max_f32_e32 v77, 0, v77
	v_pk_mul_f32 v[82:83], v[82:83], v[82:83]
	v_pk_mul_f32 v[84:85], v[84:85], v[84:85]
	v_pk_mul_f32 v[74:75], v[74:75], v[74:75]
	v_pk_mul_f32 v[76:77], v[76:77], v[76:77]
	v_cvt_pk_bf16_f32 v210, v82, v83
	v_cvt_pk_bf16_f32 v211, v84, v85
	v_cvt_pk_bf16_f32 v212, v74, v75
	v_cvt_pk_bf16_f32 v213, v76, v77
	v_add_co_u32_e32 v78, vcc, s44, v136
	v_addc_co_u32_e32 v79, vcc, 0, v137, vcc
	global_store_dwordx4 v[78:79], v[210:213], off
	v_max_f32_e32 v70, 0, v70
	v_max_f32_e32 v71, 0, v71
	v_max_f32_e32 v72, 0, v72
	v_max_f32_e32 v73, 0, v73
	v_max_f32_e32 v66, 0, v66
	v_max_f32_e32 v67, 0, v67
	v_max_f32_e32 v68, 0, v68
	v_max_f32_e32 v69, 0, v69
	v_pk_mul_f32 v[70:71], v[70:71], v[70:71]
	v_pk_mul_f32 v[72:73], v[72:73], v[72:73]
	v_pk_mul_f32 v[66:67], v[66:67], v[66:67]
	v_pk_mul_f32 v[68:69], v[68:69], v[68:69]
; __device__ __forceinline__ u32x4 pack8(const f32x4 a, const f32x4 b) { u32x4 w; w.x = cvt_pk_bf16(a[0], a[1]); w.y = cvt_pk_bf16(a[2], a[3]); w.z = cvt_pk_bf16(b[0], b[1]); w.w = cvt_pk_bf16(b[2], b[3]); return w; }
;     __device__ __forceinline__ void run(const acc_t& acc, const Unit& u, int wr, int wc, int fr, int fq, const int A0, const int A1) const {
;         const char* ub = (const char*)(U + (size_t)(u.pm * BM + wr * 64) * FF + u.pn * BM + wc * 64); const unsigned lo = (unsigned)(fr * FF + 8 * fq) * 2u;
; #pragma unroll
;         for (int ai = A0; ai < A1; ++ai)
; #pragma unroll
;             for (int m = 0; m < 4; ++m) { char* rowp = (char*)ub + (size_t)(ai * HALF + m * 16) * FF * 2;
; #pragma unroll
;                 for (int bj = 0; bj < 2; ++bj) { f32x4 a = acc[ai][bj][m][0], b = acc[ai][bj][m][1];
; #pragma unroll
;                     for (int e = 0; e < 4; ++e) { a[e] = fmaxf(a[e] * __builtin_fabsf(a[e]), 0.f); b[e] = fmaxf(b[e] * __builtin_fabsf(b[e]), 0.f); }
;                     *(u32x4*)(rowp + 32 * bj * 2 + lo) = pack8(a, b); } }
;     }
	v_cvt_pk_bf16_f32 v214, v70, v71
	v_cvt_pk_bf16_f32 v215, v72, v73
	v_cvt_pk_bf16_f32 v216, v66, v67
	v_cvt_pk_bf16_f32 v217, v68, v69
	global_store_dwordx4 v[78:79], v[214:217], off offset:64
	v_max_f32_e32 v62, 0, v62
	v_max_f32_e32 v63, 0, v63
	v_max_f32_e32 v64, 0, v64
	v_max_f32_e32 v65, 0, v65
	v_max_f32_e32 v58, 0, v58
	v_max_f32_e32 v59, 0, v59
	v_max_f32_e32 v60, 0, v60
	v_max_f32_e32 v61, 0, v61
	v_pk_mul_f32 v[62:63], v[62:63], v[62:63]
	v_pk_mul_f32 v[64:65], v[64:65], v[64:65]
	v_pk_mul_f32 v[58:59], v[58:59], v[58:59]
	v_pk_mul_f32 v[60:61], v[60:61], v[60:61]
	v_cvt_pk_bf16_f32 v210, v62, v63
	v_cvt_pk_bf16_f32 v211, v64, v65
	v_cvt_pk_bf16_f32 v212, v58, v59
	v_cvt_pk_bf16_f32 v213, v60, v61
	v_add_co_u32_e32 v62, vcc, s45, v136
	v_addc_co_u32_e32 v63, vcc, 0, v137, vcc
	global_store_dwordx4 v[62:63], v[210:213], off
	v_max_f32_e32 v54, 0, v54
	v_max_f32_e32 v55, 0, v55
	v_max_f32_e32 v56, 0, v56
	v_max_f32_e32 v57, 0, v57
	v_max_f32_e32 v46, 0, v46
	v_max_f32_e32 v47, 0, v47
	v_max_f32_e32 v48, 0, v48
	v_max_f32_e32 v49, 0, v49
	v_pk_mul_f32 v[54:55], v[54:55], v[54:55]
	v_pk_mul_f32 v[56:57], v[56:57], v[56:57]
	v_pk_mul_f32 v[46:47], v[46:47], v[46:47]
	v_pk_mul_f32 v[48:49], v[48:49], v[48:49]
	v_cvt_pk_bf16_f32 v214, v54, v55
	v_cvt_pk_bf16_f32 v215, v56, v57
	v_cvt_pk_bf16_f32 v216, v46, v47
	v_cvt_pk_bf16_f32 v217, v48, v49
	global_store_dwordx4 v[62:63], v[214:217], off offset:64
	v_max_f32_e32 v50, 0, v50
	v_max_f32_e32 v51, 0, v51
	v_max_f32_e32 v52, 0, v52
	v_max_f32_e32 v53, 0, v53
	v_max_f32_e32 v42, 0, v42
	v_max_f32_e32 v43, 0, v43
	v_max_f32_e32 v44, 0, v44
	v_max_f32_e32 v45, 0, v45
	v_pk_mul_f32 v[50:51], v[50:51], v[50:51]
	v_pk_mul_f32 v[52:53], v[52:53], v[52:53]
	v_pk_mul_f32 v[42:43], v[42:43], v[42:43]
	v_pk_mul_f32 v[44:45], v[44:45], v[44:45]
	v_cvt_pk_bf16_f32 v210, v50, v51
	v_cvt_pk_bf16_f32 v211, v52, v53
	v_cvt_pk_bf16_f32 v212, v42, v43
	v_cvt_pk_bf16_f32 v213, v44, v45
	v_add_co_u32_e32 v46, vcc, s46, v136
	v_addc_co_u32_e32 v47, vcc, 0, v137, vcc
	global_store_dwordx4 v[46:47], v[210:213], off
	v_max_f32_e32 v38, 0, v38
	v_max_f32_e32 v39, 0, v39
	v_max_f32_e32 v40, 0, v40
	v_max_f32_e32 v41, 0, v41
	v_max_f32_e32 v30, 0, v30
	v_max_f32_e32 v31, 0, v31
	v_max_f32_e32 v32, 0, v32
	v_max_f32_e32 v33, 0, v33
	v_pk_mul_f32 v[38:39], v[38:39], v[38:39]
	v_pk_mul_f32 v[40:41], v[40:41], v[40:41]
	v_pk_mul_f32 v[30:31], v[30:31], v[30:31]
	v_pk_mul_f32 v[32:33], v[32:33], v[32:33]
	v_cvt_pk_bf16_f32 v214, v38, v39
	v_cvt_pk_bf16_f32 v215, v40, v41
	v_cvt_pk_bf16_f32 v216, v30, v31
	v_cvt_pk_bf16_f32 v217, v32, v33
	global_store_dwordx4 v[46:47], v[214:217], off offset:64
	v_max_f32_e32 v34, 0, v34
	v_max_f32_e32 v35, 0, v35
	v_max_f32_e32 v36, 0, v36
	v_max_f32_e32 v37, 0, v37
	v_max_f32_e32 v26, 0, v26
	v_max_f32_e32 v27, 0, v27
	v_max_f32_e32 v28, 0, v28
	v_max_f32_e32 v29, 0, v29
	v_pk_mul_f32 v[34:35], v[34:35], v[34:35]
	v_pk_mul_f32 v[36:37], v[36:37], v[36:37]
	v_pk_mul_f32 v[26:27], v[26:27], v[26:27]
	v_pk_mul_f32 v[28:29], v[28:29], v[28:29]
	v_cvt_pk_bf16_f32 v210, v34, v35
	v_cvt_pk_bf16_f32 v211, v36, v37
	v_cvt_pk_bf16_f32 v212, v26, v27
	v_cvt_pk_bf16_f32 v213, v28, v29
	v_add_co_u32_e32 v30, vcc, s47, v136
	v_addc_co_u32_e32 v31, vcc, 0, v137, vcc
	global_store_dwordx4 v[30:31], v[210:213], off
	v_max_f32_e32 v22, 0, v22
	v_max_f32_e32 v23, 0, v23
	v_max_f32_e32 v24, 0, v24
	v_max_f32_e32 v25, 0, v25
	v_max_f32_e32 v14, 0, v14
	v_max_f32_e32 v15, 0, v15
	v_max_f32_e32 v16, 0, v16
	v_max_f32_e32 v17, 0, v17
	v_pk_mul_f32 v[22:23], v[22:23], v[22:23]
	v_pk_mul_f32 v[24:25], v[24:25], v[24:25]
	v_pk_mul_f32 v[14:15], v[14:15], v[14:15]
	v_pk_mul_f32 v[16:17], v[16:17], v[16:17]
	v_cvt_pk_bf16_f32 v214, v22, v23
	v_cvt_pk_bf16_f32 v215, v24, v25
	v_cvt_pk_bf16_f32 v216, v14, v15
	v_cvt_pk_bf16_f32 v217, v16, v17
	global_store_dwordx4 v[30:31], v[214:217], off offset:64
	v_max_f32_e32 v18, 0, v18
	v_max_f32_e32 v19, 0, v19
	v_max_f32_e32 v20, 0, v20
	v_max_f32_e32 v21, 0, v21
	v_max_f32_e32 v10, 0, v10
	v_max_f32_e32 v11, 0, v11
	v_max_f32_e32 v12, 0, v12
	v_max_f32_e32 v13, 0, v13
	v_pk_mul_f32 v[18:19], v[18:19], v[18:19]
	v_pk_mul_f32 v[20:21], v[20:21], v[20:21]
	v_pk_mul_f32 v[10:11], v[10:11], v[10:11]
	v_pk_mul_f32 v[12:13], v[12:13], v[12:13]
	v_cvt_pk_bf16_f32 v210, v18, v19
	v_cvt_pk_bf16_f32 v211, v20, v21
	v_cvt_pk_bf16_f32 v212, v10, v11
	v_cvt_pk_bf16_f32 v213, v12, v13
	v_add_co_u32_e32 v14, vcc, s48, v136
	v_addc_co_u32_e32 v15, vcc, 0, v137, vcc
	global_store_dwordx4 v[14:15], v[210:213], off
	v_max_f32_e32 v6, 0, v6
	v_max_f32_e32 v7, 0, v7
	v_max_f32_e32 v8, 0, v8
	v_max_f32_e32 v9, 0, v9
	v_max_f32_e32 v2, 0, v2
	v_max_f32_e32 v3, 0, v3
	v_max_f32_e32 v4, 0, v4
	v_max_f32_e32 v5, 0, v5
	v_pk_mul_f32 v[6:7], v[6:7], v[6:7]
	v_pk_mul_f32 v[8:9], v[8:9], v[8:9]
	v_pk_mul_f32 v[2:3], v[2:3], v[2:3]
	v_pk_mul_f32 v[4:5], v[4:5], v[4:5]
	v_cvt_pk_bf16_f32 v214, v6, v7
	v_cvt_pk_bf16_f32 v215, v8, v9
	v_cvt_pk_bf16_f32 v216, v2, v3
	v_cvt_pk_bf16_f32 v217, v4, v5
	s_andn2_b64 vcc, exec, s[4:5]
	s_mov_b64 s[4:5], -1
	global_store_dwordx4 v[14:15], v[214:217], off offset:64
	s_cbranch_vccnz .LBB0_887
	s_andn2_b64 vcc, exec, s[0:1]
	s_cbranch_vccnz .LBB0_886
	s_barrier
	s_branch .LBB0_886
